# GEMM unit loop: accumulators cleared with 64 two-register moves
# speedup vs baseline: 1.0151x; 1.0073x over previous
.LBB11_220:
	s_add_u32 s12, s30, s59
	s_addc_u32 s13, s31, 0
	s_and_b64 s[18:19], s[16:17], exec
	s_cselect_b32 s7, s13, s21
	s_cselect_b32 s26, s12, s20
	s_add_u32 s18, s34, s57
	s_addc_u32 s19, s35, 0
	s_and_b64 s[24:25], s[16:17], exec
	s_cselect_b32 s27, s19, s23
	s_cselect_b32 s60, s18, s22
	s_add_u32 s20, s20, 0x40080
	s_addc_u32 s21, s21, 0
	s_add_u32 s61, s22, 0x100
	v_mov_b32_e32 v0, 0
	s_addc_u32 s62, s23, 0
	s_mov_b32 s63, -2
	v_mov_b64_e32 v[0:1], 0
	v_mov_b64_e32 v[2:3], 0
	v_mov_b64_e32 v[4:5], 0
	v_mov_b64_e32 v[6:7], 0
	v_mov_b64_e32 v[8:9], 0
	v_mov_b64_e32 v[10:11], 0
	v_mov_b64_e32 v[12:13], 0
	v_mov_b64_e32 v[14:15], 0
	v_mov_b64_e32 v[16:17], 0
	v_mov_b64_e32 v[18:19], 0
	v_mov_b64_e32 v[20:21], 0
	v_mov_b64_e32 v[22:23], 0
	v_mov_b64_e32 v[24:25], 0
	v_mov_b64_e32 v[26:27], 0
	v_mov_b64_e32 v[28:29], 0
	v_mov_b64_e32 v[30:31], 0
	v_mov_b64_e32 v[32:33], 0
	v_mov_b64_e32 v[34:35], 0
	v_mov_b64_e32 v[36:37], 0
	v_mov_b64_e32 v[38:39], 0
	v_mov_b64_e32 v[40:41], 0
	v_mov_b64_e32 v[42:43], 0
	v_mov_b64_e32 v[44:45], 0
	v_mov_b64_e32 v[46:47], 0
	v_mov_b64_e32 v[48:49], 0
	v_mov_b64_e32 v[50:51], 0
	v_mov_b64_e32 v[52:53], 0
	v_mov_b64_e32 v[54:55], 0
	v_mov_b64_e32 v[56:57], 0
	v_mov_b64_e32 v[58:59], 0
	v_mov_b64_e32 v[60:61], 0
	v_mov_b64_e32 v[62:63], 0
	v_mov_b64_e32 v[64:65], 0
	v_mov_b64_e32 v[66:67], 0
	v_mov_b64_e32 v[68:69], 0
	v_mov_b64_e32 v[70:71], 0
	v_mov_b64_e32 v[72:73], 0
	v_mov_b64_e32 v[74:75], 0
	v_mov_b64_e32 v[76:77], 0
	v_mov_b64_e32 v[78:79], 0
	v_mov_b64_e32 v[80:81], 0
	v_mov_b64_e32 v[82:83], 0
	v_mov_b64_e32 v[84:85], 0
	v_mov_b64_e32 v[86:87], 0
	v_mov_b64_e32 v[88:89], 0
	v_mov_b64_e32 v[90:91], 0
	v_mov_b64_e32 v[92:93], 0
	v_mov_b64_e32 v[94:95], 0
	v_mov_b64_e32 v[96:97], 0
	v_mov_b64_e32 v[98:99], 0
	v_mov_b64_e32 v[100:101], 0
	v_mov_b64_e32 v[102:103], 0
	v_mov_b64_e32 v[104:105], 0
	v_mov_b64_e32 v[106:107], 0
	v_mov_b64_e32 v[108:109], 0
	v_mov_b64_e32 v[110:111], 0
	v_mov_b64_e32 v[112:113], 0
	v_mov_b64_e32 v[114:115], 0
	v_mov_b64_e32 v[116:117], 0
	v_mov_b64_e32 v[118:119], 0
	v_mov_b64_e32 v[120:121], 0
	v_mov_b64_e32 v[122:123], 0
	v_mov_b64_e32 v[124:125], 0
	v_mov_b64_e32 v[126:127], 0

.LBB11_925:
	v_readlane_b32 s0, v243, 26
	s_add_u32 s18, s0, s44
	v_readlane_b32 s0, v243, 27
	s_addc_u32 s19, s0, 0
	s_and_b64 s[0:1], s[16:17], exec
	s_cselect_b32 s8, s19, s23
	s_cselect_b32 s9, s18, s22
	s_add_u32 s20, s30, s43
	s_addc_u32 s21, s31, 0
	s_and_b64 s[0:1], s[16:17], exec
	s_cselect_b32 s40, s21, s25
	s_cselect_b32 s46, s20, s24
	s_add_u32 s22, s22, 0x40080
	s_addc_u32 s23, s23, 0
	s_add_u32 s47, s24, 0x100
	v_mov_b32_e32 v2, 0
	s_addc_u32 s56, s25, 0
	s_mov_b32 s57, -2
	s_waitcnt lgkmcnt(0)
	v_mov_b64_e32 v[2:3], 0
	v_mov_b64_e32 v[4:5], 0
	v_mov_b64_e32 v[6:7], 0
	v_mov_b64_e32 v[8:9], 0
	v_mov_b64_e32 v[10:11], 0
	v_mov_b64_e32 v[12:13], 0
	v_mov_b64_e32 v[14:15], 0
	v_mov_b64_e32 v[16:17], 0
	v_mov_b64_e32 v[18:19], 0
	v_mov_b64_e32 v[20:21], 0
	v_mov_b64_e32 v[22:23], 0
	v_mov_b64_e32 v[24:25], 0
	v_mov_b64_e32 v[26:27], 0
	v_mov_b64_e32 v[28:29], 0
	v_mov_b64_e32 v[30:31], 0
	v_mov_b64_e32 v[32:33], 0
	v_mov_b64_e32 v[34:35], 0
	v_mov_b64_e32 v[36:37], 0
	v_mov_b64_e32 v[38:39], 0
	v_mov_b64_e32 v[40:41], 0
	v_mov_b64_e32 v[42:43], 0
	v_mov_b64_e32 v[44:45], 0
	v_mov_b64_e32 v[46:47], 0
	v_mov_b64_e32 v[48:49], 0
	v_mov_b64_e32 v[50:51], 0
	v_mov_b64_e32 v[52:53], 0
	v_mov_b64_e32 v[54:55], 0
	v_mov_b64_e32 v[56:57], 0
	v_mov_b64_e32 v[58:59], 0
	v_mov_b64_e32 v[60:61], 0
	v_mov_b64_e32 v[62:63], 0
	v_mov_b64_e32 v[64:65], 0
	v_mov_b64_e32 v[66:67], 0
	v_mov_b64_e32 v[68:69], 0
	v_mov_b64_e32 v[70:71], 0
	v_mov_b64_e32 v[72:73], 0
	v_mov_b64_e32 v[74:75], 0
	v_mov_b64_e32 v[76:77], 0
	v_mov_b64_e32 v[78:79], 0
	v_mov_b64_e32 v[80:81], 0
	v_mov_b64_e32 v[82:83], 0
	v_mov_b64_e32 v[84:85], 0
	v_mov_b64_e32 v[86:87], 0
	v_mov_b64_e32 v[88:89], 0
	v_mov_b64_e32 v[90:91], 0
	v_mov_b64_e32 v[92:93], 0
	v_mov_b64_e32 v[94:95], 0
	v_mov_b64_e32 v[96:97], 0
	v_mov_b64_e32 v[98:99], 0
	v_mov_b64_e32 v[100:101], 0
	v_mov_b64_e32 v[102:103], 0
	v_mov_b64_e32 v[104:105], 0
	v_mov_b64_e32 v[106:107], 0
	v_mov_b64_e32 v[108:109], 0
	v_mov_b64_e32 v[110:111], 0
	v_mov_b64_e32 v[112:113], 0
	v_mov_b64_e32 v[114:115], 0
	v_mov_b64_e32 v[116:117], 0
	v_mov_b64_e32 v[118:119], 0
	v_mov_b64_e32 v[120:121], 0
	v_mov_b64_e32 v[122:123], 0
	v_mov_b64_e32 v[124:125], 0
	v_mov_b64_e32 v[126:127], 0
	v_mov_b64_e32 v[128:129], 0

.LBB11_1171:
	s_add_u32 s24, s66, s91
	s_addc_u32 s25, s67, 0
	s_and_b64 s[0:1], s[22:23], exec
	s_cselect_b32 s9, s25, s17
	s_cselect_b32 s68, s24, s16
	s_add_u32 s26, s36, s90
	s_addc_u32 s27, s37, 0
	s_and_b64 s[0:1], s[22:23], exec
	s_cselect_b32 s69, s27, s29
	s_cselect_b32 s70, s26, s28
	s_add_u32 s16, s16, 0x40080
	s_addc_u32 s17, s17, 0
	s_add_u32 s71, s28, 0x100
	v_mov_b32_e32 v2, 0
	s_addc_u32 vcc_lo, s29, 0
	s_mov_b32 vcc_hi, -2
	s_waitcnt lgkmcnt(0)
	v_mov_b64_e32 v[2:3], 0
	v_mov_b64_e32 v[4:5], 0
	v_mov_b64_e32 v[6:7], 0
	v_mov_b64_e32 v[8:9], 0
	v_mov_b64_e32 v[10:11], 0
	v_mov_b64_e32 v[12:13], 0
	v_mov_b64_e32 v[14:15], 0
	v_mov_b64_e32 v[16:17], 0
	v_mov_b64_e32 v[18:19], 0
	v_mov_b64_e32 v[20:21], 0
	v_mov_b64_e32 v[22:23], 0
	v_mov_b64_e32 v[24:25], 0
	v_mov_b64_e32 v[26:27], 0
	v_mov_b64_e32 v[28:29], 0
	v_mov_b64_e32 v[30:31], 0
	v_mov_b64_e32 v[32:33], 0
	v_mov_b64_e32 v[34:35], 0
	v_mov_b64_e32 v[36:37], 0
	v_mov_b64_e32 v[38:39], 0
	v_mov_b64_e32 v[40:41], 0
	v_mov_b64_e32 v[42:43], 0
	v_mov_b64_e32 v[44:45], 0
	v_mov_b64_e32 v[46:47], 0
	v_mov_b64_e32 v[48:49], 0
	v_mov_b64_e32 v[50:51], 0
	v_mov_b64_e32 v[52:53], 0
	v_mov_b64_e32 v[54:55], 0
	v_mov_b64_e32 v[56:57], 0
	v_mov_b64_e32 v[58:59], 0
	v_mov_b64_e32 v[60:61], 0
	v_mov_b64_e32 v[62:63], 0
	v_mov_b64_e32 v[64:65], 0
	v_mov_b64_e32 v[66:67], 0
	v_mov_b64_e32 v[68:69], 0
	v_mov_b64_e32 v[70:71], 0
	v_mov_b64_e32 v[72:73], 0
	v_mov_b64_e32 v[74:75], 0
	v_mov_b64_e32 v[76:77], 0
	v_mov_b64_e32 v[78:79], 0
	v_mov_b64_e32 v[80:81], 0
	v_mov_b64_e32 v[82:83], 0
	v_mov_b64_e32 v[84:85], 0
	v_mov_b64_e32 v[86:87], 0
	v_mov_b64_e32 v[88:89], 0
	v_mov_b64_e32 v[90:91], 0
	v_mov_b64_e32 v[92:93], 0
	v_mov_b64_e32 v[94:95], 0
	v_mov_b64_e32 v[96:97], 0
	v_mov_b64_e32 v[98:99], 0
	v_mov_b64_e32 v[100:101], 0
	v_mov_b64_e32 v[102:103], 0
	v_mov_b64_e32 v[104:105], 0
	v_mov_b64_e32 v[106:107], 0
	v_mov_b64_e32 v[108:109], 0
	v_mov_b64_e32 v[110:111], 0
	v_mov_b64_e32 v[112:113], 0
	v_mov_b64_e32 v[114:115], 0
	v_mov_b64_e32 v[116:117], 0
	v_mov_b64_e32 v[118:119], 0
	v_mov_b64_e32 v[120:121], 0
	v_mov_b64_e32 v[122:123], 0
	v_mov_b64_e32 v[124:125], 0
	v_mov_b64_e32 v[126:127], 0
	v_mov_b64_e32 v[128:129], 0

.LBB11_1628:
	v_readlane_b32 s0, v243, 39
	s_add_u32 s18, s0, s44
	v_readlane_b32 s0, v243, 40
	s_addc_u32 s19, s0, 0
	s_and_b64 s[0:1], s[16:17], exec
	s_cselect_b32 s8, s19, s23
	s_cselect_b32 s9, s18, s22
	s_add_u32 s20, s30, s43
	s_addc_u32 s21, s31, 0
	s_and_b64 s[0:1], s[16:17], exec
	s_cselect_b32 s40, s21, s25
	s_cselect_b32 s46, s20, s24
	s_add_u32 s22, s22, 0x80080
	s_addc_u32 s23, s23, 0
	s_add_u32 s47, s24, 0x100
	v_mov_b32_e32 v2, 0
	s_addc_u32 s56, s25, 0
	s_mov_b32 s57, -2
	s_waitcnt lgkmcnt(0)
	v_mov_b64_e32 v[2:3], 0
	v_mov_b64_e32 v[4:5], 0
	v_mov_b64_e32 v[6:7], 0
	v_mov_b64_e32 v[8:9], 0
	v_mov_b64_e32 v[10:11], 0
	v_mov_b64_e32 v[12:13], 0
	v_mov_b64_e32 v[14:15], 0
	v_mov_b64_e32 v[16:17], 0
	v_mov_b64_e32 v[18:19], 0
	v_mov_b64_e32 v[20:21], 0
	v_mov_b64_e32 v[22:23], 0
	v_mov_b64_e32 v[24:25], 0
	v_mov_b64_e32 v[26:27], 0
	v_mov_b64_e32 v[28:29], 0
	v_mov_b64_e32 v[30:31], 0
	v_mov_b64_e32 v[32:33], 0
	v_mov_b64_e32 v[34:35], 0
	v_mov_b64_e32 v[36:37], 0
	v_mov_b64_e32 v[38:39], 0
	v_mov_b64_e32 v[40:41], 0
	v_mov_b64_e32 v[42:43], 0
	v_mov_b64_e32 v[44:45], 0
	v_mov_b64_e32 v[46:47], 0
	v_mov_b64_e32 v[48:49], 0
	v_mov_b64_e32 v[50:51], 0
	v_mov_b64_e32 v[52:53], 0
	v_mov_b64_e32 v[54:55], 0
	v_mov_b64_e32 v[56:57], 0
	v_mov_b64_e32 v[58:59], 0
	v_mov_b64_e32 v[60:61], 0
	v_mov_b64_e32 v[62:63], 0
	v_mov_b64_e32 v[64:65], 0
	v_mov_b64_e32 v[66:67], 0
	v_mov_b64_e32 v[68:69], 0
	v_mov_b64_e32 v[70:71], 0
	v_mov_b64_e32 v[72:73], 0
	v_mov_b64_e32 v[74:75], 0
	v_mov_b64_e32 v[76:77], 0
	v_mov_b64_e32 v[78:79], 0
	v_mov_b64_e32 v[80:81], 0
	v_mov_b64_e32 v[82:83], 0
	v_mov_b64_e32 v[84:85], 0
	v_mov_b64_e32 v[86:87], 0
	v_mov_b64_e32 v[88:89], 0
	v_mov_b64_e32 v[90:91], 0
	v_mov_b64_e32 v[92:93], 0
	v_mov_b64_e32 v[94:95], 0
	v_mov_b64_e32 v[96:97], 0
	v_mov_b64_e32 v[98:99], 0
	v_mov_b64_e32 v[100:101], 0
	v_mov_b64_e32 v[102:103], 0
	v_mov_b64_e32 v[104:105], 0
	v_mov_b64_e32 v[106:107], 0
	v_mov_b64_e32 v[108:109], 0
	v_mov_b64_e32 v[110:111], 0
	v_mov_b64_e32 v[112:113], 0
	v_mov_b64_e32 v[114:115], 0
	v_mov_b64_e32 v[116:117], 0
	v_mov_b64_e32 v[118:119], 0
	v_mov_b64_e32 v[120:121], 0
	v_mov_b64_e32 v[122:123], 0
	v_mov_b64_e32 v[124:125], 0
	v_mov_b64_e32 v[126:127], 0
	v_mov_b64_e32 v[128:129], 0

.LBB11_1868:
	s_add_u32 s20, s66, s40
	s_addc_u32 s21, s67, 0
	s_and_b64 s[0:1], exec, s[18:19]
	s_cselect_b32 s43, s21, s25
	s_cselect_b32 s44, s20, s24
	s_add_u32 s22, s34, s22
	s_addc_u32 s23, s35, s23
	s_and_b64 s[0:1], exec, s[18:19]
	s_cselect_b32 s45, s23, s11
	s_cselect_b32 s46, s22, s10
	s_add_u32 s24, s24, 0x40080
	s_addc_u32 s25, s25, 0
	s_add_u32 s47, s10, 0x100
	v_mov_b32_e32 v2, 0
	s_addc_u32 s56, s11, 0
	s_mov_b32 s57, -2
	v_mov_b64_e32 v[2:3], 0
	v_mov_b64_e32 v[4:5], 0
	v_mov_b64_e32 v[6:7], 0
	v_mov_b64_e32 v[8:9], 0
	v_mov_b64_e32 v[10:11], 0
	v_mov_b64_e32 v[12:13], 0
	v_mov_b64_e32 v[14:15], 0
	v_mov_b64_e32 v[16:17], 0
	v_mov_b64_e32 v[18:19], 0
	v_mov_b64_e32 v[20:21], 0
	v_mov_b64_e32 v[22:23], 0
	v_mov_b64_e32 v[24:25], 0
	v_mov_b64_e32 v[26:27], 0
	v_mov_b64_e32 v[28:29], 0
	v_mov_b64_e32 v[30:31], 0
	v_mov_b64_e32 v[32:33], 0
	v_mov_b64_e32 v[34:35], 0
	v_mov_b64_e32 v[36:37], 0
	v_mov_b64_e32 v[38:39], 0
	v_mov_b64_e32 v[40:41], 0
	v_mov_b64_e32 v[42:43], 0
	v_mov_b64_e32 v[44:45], 0
	v_mov_b64_e32 v[46:47], 0
	v_mov_b64_e32 v[48:49], 0
	v_mov_b64_e32 v[50:51], 0
	v_mov_b64_e32 v[52:53], 0
	v_mov_b64_e32 v[54:55], 0
	v_mov_b64_e32 v[56:57], 0
	v_mov_b64_e32 v[58:59], 0
	v_mov_b64_e32 v[60:61], 0
	v_mov_b64_e32 v[62:63], 0
	v_mov_b64_e32 v[64:65], 0
	v_mov_b64_e32 v[66:67], 0
	v_mov_b64_e32 v[68:69], 0
	v_mov_b64_e32 v[70:71], 0
	v_mov_b64_e32 v[72:73], 0
	v_mov_b64_e32 v[74:75], 0
	v_mov_b64_e32 v[76:77], 0
	v_mov_b64_e32 v[78:79], 0
	v_mov_b64_e32 v[80:81], 0
	v_mov_b64_e32 v[82:83], 0
	v_mov_b64_e32 v[84:85], 0
	v_mov_b64_e32 v[86:87], 0
	v_mov_b64_e32 v[88:89], 0
	v_mov_b64_e32 v[90:91], 0
	v_mov_b64_e32 v[92:93], 0
	v_mov_b64_e32 v[94:95], 0
	v_mov_b64_e32 v[96:97], 0
	v_mov_b64_e32 v[98:99], 0
	v_mov_b64_e32 v[100:101], 0
	v_mov_b64_e32 v[102:103], 0
	v_mov_b64_e32 v[104:105], 0
	v_mov_b64_e32 v[106:107], 0
	v_mov_b64_e32 v[108:109], 0
	v_mov_b64_e32 v[110:111], 0
	v_mov_b64_e32 v[112:113], 0
	v_mov_b64_e32 v[114:115], 0
	v_mov_b64_e32 v[116:117], 0
	v_mov_b64_e32 v[118:119], 0
	v_mov_b64_e32 v[120:121], 0
	v_mov_b64_e32 v[122:123], 0
	v_mov_b64_e32 v[124:125], 0
	v_mov_b64_e32 v[126:127], 0
	v_mov_b64_e32 v[128:129], 0

.LBB11_2044:
	s_add_u32 s18, s78, s91
	s_addc_u32 s19, s79, 0
	s_and_b64 s[0:1], s[20:21], exec
	s_cselect_b32 s7, s19, s27
	s_cselect_b32 s8, s18, s26
	s_add_u32 s22, s44, s29
	s_addc_u32 s23, s45, 0
	s_and_b64 s[0:1], s[20:21], exec
	v_mov_b32_e32 v2, 0
	s_cselect_b32 s9, s23, s25
	s_cselect_b32 s68, s22, s24
	s_mov_b64 s[34:35], 0
	s_mov_b64 s[30:31], -1
	s_mov_b64 s[10:11], 0
	v_mov_b64_e32 v[2:3], 0
	v_mov_b64_e32 v[4:5], 0
	v_mov_b64_e32 v[6:7], 0
	v_mov_b64_e32 v[8:9], 0
	v_mov_b64_e32 v[10:11], 0
	v_mov_b64_e32 v[12:13], 0
	v_mov_b64_e32 v[14:15], 0
	v_mov_b64_e32 v[16:17], 0
	v_mov_b64_e32 v[18:19], 0
	v_mov_b64_e32 v[20:21], 0
	v_mov_b64_e32 v[22:23], 0
	v_mov_b64_e32 v[24:25], 0
	v_mov_b64_e32 v[26:27], 0
	v_mov_b64_e32 v[28:29], 0
	v_mov_b64_e32 v[30:31], 0
	v_mov_b64_e32 v[32:33], 0
	v_mov_b64_e32 v[34:35], 0
	v_mov_b64_e32 v[36:37], 0
	v_mov_b64_e32 v[38:39], 0
	v_mov_b64_e32 v[40:41], 0
	v_mov_b64_e32 v[42:43], 0
	v_mov_b64_e32 v[44:45], 0
	v_mov_b64_e32 v[46:47], 0
	v_mov_b64_e32 v[48:49], 0
	v_mov_b64_e32 v[50:51], 0
	v_mov_b64_e32 v[52:53], 0
	v_mov_b64_e32 v[54:55], 0
	v_mov_b64_e32 v[56:57], 0
	v_mov_b64_e32 v[58:59], 0
	v_mov_b64_e32 v[60:61], 0
	v_mov_b64_e32 v[62:63], 0
	v_mov_b64_e32 v[64:65], 0
	v_mov_b64_e32 v[66:67], 0
	v_mov_b64_e32 v[68:69], 0
	v_mov_b64_e32 v[70:71], 0
	v_mov_b64_e32 v[72:73], 0
	v_mov_b64_e32 v[74:75], 0
	v_mov_b64_e32 v[76:77], 0
	v_mov_b64_e32 v[78:79], 0
	v_mov_b64_e32 v[80:81], 0
	v_mov_b64_e32 v[82:83], 0
	v_mov_b64_e32 v[84:85], 0
	v_mov_b64_e32 v[86:87], 0
	v_mov_b64_e32 v[88:89], 0
	v_mov_b64_e32 v[90:91], 0
	v_mov_b64_e32 v[92:93], 0
	v_mov_b64_e32 v[94:95], 0
	v_mov_b64_e32 v[96:97], 0
	v_mov_b64_e32 v[98:99], 0
	v_mov_b64_e32 v[100:101], 0
	v_mov_b64_e32 v[102:103], 0
	v_mov_b64_e32 v[104:105], 0
	v_mov_b64_e32 v[106:107], 0
	v_mov_b64_e32 v[108:109], 0
	v_mov_b64_e32 v[110:111], 0
	v_mov_b64_e32 v[112:113], 0
	v_mov_b64_e32 v[114:115], 0
	v_mov_b64_e32 v[116:117], 0
	v_mov_b64_e32 v[118:119], 0
	v_mov_b64_e32 v[120:121], 0
	v_mov_b64_e32 v[122:123], 0
	v_mov_b64_e32 v[124:125], 0
	v_mov_b64_e32 v[126:127], 0
	v_mov_b64_e32 v[128:129], 0

.LBB11_2092:
	s_add_u32 s16, s80, s9
	s_addc_u32 s17, s81, 0
	s_and_b64 s[0:1], s[18:19], exec
	s_cselect_b32 s58, s17, s25
	s_cselect_b32 s59, s16, s24
	s_add_u32 s20, s6, s56
	s_addc_u32 s21, s7, 0
	s_and_b64 s[0:1], s[18:19], exec
	v_mov_b32_e32 v2, 0
	s_cselect_b32 s60, s21, s23
	s_cselect_b32 s68, s20, s22
	s_mov_b64 s[28:29], 0
	s_mov_b64 s[26:27], -1
	s_mov_b64 s[10:11], 0
	v_mov_b64_e32 v[2:3], 0
	v_mov_b64_e32 v[4:5], 0
	v_mov_b64_e32 v[6:7], 0
	v_mov_b64_e32 v[8:9], 0
	v_mov_b64_e32 v[10:11], 0
	v_mov_b64_e32 v[12:13], 0
	v_mov_b64_e32 v[14:15], 0
	v_mov_b64_e32 v[16:17], 0
	v_mov_b64_e32 v[18:19], 0
	v_mov_b64_e32 v[20:21], 0
	v_mov_b64_e32 v[22:23], 0
	v_mov_b64_e32 v[24:25], 0
	v_mov_b64_e32 v[26:27], 0
	v_mov_b64_e32 v[28:29], 0
	v_mov_b64_e32 v[30:31], 0
	v_mov_b64_e32 v[32:33], 0
	v_mov_b64_e32 v[34:35], 0
	v_mov_b64_e32 v[36:37], 0
	v_mov_b64_e32 v[38:39], 0
	v_mov_b64_e32 v[40:41], 0
	v_mov_b64_e32 v[42:43], 0
	v_mov_b64_e32 v[44:45], 0
	v_mov_b64_e32 v[46:47], 0
	v_mov_b64_e32 v[48:49], 0
	v_mov_b64_e32 v[50:51], 0
	v_mov_b64_e32 v[52:53], 0
	v_mov_b64_e32 v[54:55], 0
	v_mov_b64_e32 v[56:57], 0
	v_mov_b64_e32 v[58:59], 0
	v_mov_b64_e32 v[60:61], 0
	v_mov_b64_e32 v[62:63], 0
	v_mov_b64_e32 v[64:65], 0
	v_mov_b64_e32 v[66:67], 0
	v_mov_b64_e32 v[68:69], 0
	v_mov_b64_e32 v[70:71], 0
	v_mov_b64_e32 v[72:73], 0
	v_mov_b64_e32 v[74:75], 0
	v_mov_b64_e32 v[76:77], 0
	v_mov_b64_e32 v[78:79], 0
	v_mov_b64_e32 v[80:81], 0
	v_mov_b64_e32 v[82:83], 0
	v_mov_b64_e32 v[84:85], 0
	v_mov_b64_e32 v[86:87], 0
	v_mov_b64_e32 v[88:89], 0
	v_mov_b64_e32 v[90:91], 0
	v_mov_b64_e32 v[92:93], 0
	v_mov_b64_e32 v[94:95], 0
	v_mov_b64_e32 v[96:97], 0
	v_mov_b64_e32 v[98:99], 0
	v_mov_b64_e32 v[100:101], 0
	v_mov_b64_e32 v[102:103], 0
	v_mov_b64_e32 v[104:105], 0
	v_mov_b64_e32 v[106:107], 0
	v_mov_b64_e32 v[108:109], 0
	v_mov_b64_e32 v[110:111], 0
	v_mov_b64_e32 v[112:113], 0
	v_mov_b64_e32 v[114:115], 0
	v_mov_b64_e32 v[116:117], 0
	v_mov_b64_e32 v[118:119], 0
	v_mov_b64_e32 v[120:121], 0
	v_mov_b64_e32 v[122:123], 0
	v_mov_b64_e32 v[124:125], 0
	v_mov_b64_e32 v[126:127], 0
	v_mov_b64_e32 v[128:129], 0

.LBB11_2328:
	s_add_u32 s18, s82, s43
	s_addc_u32 s19, s83, 0
	s_and_b64 s[0:1], s[16:17], exec
	s_cselect_b32 s8, s19, s23
	s_cselect_b32 s9, s18, s22
	s_add_u32 s20, s30, s42
	s_addc_u32 s21, s31, 0
	s_and_b64 s[0:1], s[16:17], exec
	s_cselect_b32 s45, s21, s25
	s_cselect_b32 s46, s20, s24
	s_add_u32 s22, s22, 0x40080
	s_addc_u32 s23, s23, 0
	s_add_u32 s47, s24, 0x100
	v_mov_b32_e32 v2, 0
	s_addc_u32 s56, s25, 0
	s_mov_b32 s57, -2
	s_waitcnt lgkmcnt(0)
	v_mov_b64_e32 v[2:3], 0
	v_mov_b64_e32 v[4:5], 0
	v_mov_b64_e32 v[6:7], 0
	v_mov_b64_e32 v[8:9], 0
	v_mov_b64_e32 v[10:11], 0
	v_mov_b64_e32 v[12:13], 0
	v_mov_b64_e32 v[14:15], 0
	v_mov_b64_e32 v[16:17], 0
	v_mov_b64_e32 v[18:19], 0
	v_mov_b64_e32 v[20:21], 0
	v_mov_b64_e32 v[22:23], 0
	v_mov_b64_e32 v[24:25], 0
	v_mov_b64_e32 v[26:27], 0
	v_mov_b64_e32 v[28:29], 0
	v_mov_b64_e32 v[30:31], 0
	v_mov_b64_e32 v[32:33], 0
	v_mov_b64_e32 v[34:35], 0
	v_mov_b64_e32 v[36:37], 0
	v_mov_b64_e32 v[38:39], 0
	v_mov_b64_e32 v[40:41], 0
	v_mov_b64_e32 v[42:43], 0
	v_mov_b64_e32 v[44:45], 0
	v_mov_b64_e32 v[46:47], 0
	v_mov_b64_e32 v[48:49], 0
	v_mov_b64_e32 v[50:51], 0
	v_mov_b64_e32 v[52:53], 0
	v_mov_b64_e32 v[54:55], 0
	v_mov_b64_e32 v[56:57], 0
	v_mov_b64_e32 v[58:59], 0
	v_mov_b64_e32 v[60:61], 0
	v_mov_b64_e32 v[62:63], 0
	v_mov_b64_e32 v[64:65], 0
	v_mov_b64_e32 v[66:67], 0
	v_mov_b64_e32 v[68:69], 0
	v_mov_b64_e32 v[70:71], 0
	v_mov_b64_e32 v[72:73], 0
	v_mov_b64_e32 v[74:75], 0
	v_mov_b64_e32 v[76:77], 0
	v_mov_b64_e32 v[78:79], 0
	v_mov_b64_e32 v[80:81], 0
	v_mov_b64_e32 v[82:83], 0
	v_mov_b64_e32 v[84:85], 0
	v_mov_b64_e32 v[86:87], 0
	v_mov_b64_e32 v[88:89], 0
	v_mov_b64_e32 v[90:91], 0
	v_mov_b64_e32 v[92:93], 0
	v_mov_b64_e32 v[94:95], 0
	v_mov_b64_e32 v[96:97], 0
	v_mov_b64_e32 v[98:99], 0
	v_mov_b64_e32 v[100:101], 0
	v_mov_b64_e32 v[102:103], 0
	v_mov_b64_e32 v[104:105], 0
	v_mov_b64_e32 v[106:107], 0
	v_mov_b64_e32 v[108:109], 0
	v_mov_b64_e32 v[110:111], 0
	v_mov_b64_e32 v[112:113], 0
	v_mov_b64_e32 v[114:115], 0
	v_mov_b64_e32 v[116:117], 0
	v_mov_b64_e32 v[118:119], 0
	v_mov_b64_e32 v[120:121], 0
	v_mov_b64_e32 v[122:123], 0
	v_mov_b64_e32 v[124:125], 0
	v_mov_b64_e32 v[126:127], 0
	v_mov_b64_e32 v[128:129], 0

.LBB11_2566:
	s_add_u32 s22, s66, s45
	s_addc_u32 s23, s67, 0
	s_and_b64 s[0:1], s[12:13], exec
	s_cselect_b32 s9, s23, s27
	s_cselect_b32 s47, s22, s26
	s_add_u32 s24, s14, s44
	s_addc_u32 s25, s15, 0
	s_and_b64 s[0:1], s[12:13], exec
	s_cselect_b32 s56, s25, s29
	s_cselect_b32 s57, s24, s28
	s_add_u32 s26, s26, 0x40080
	s_addc_u32 s27, s27, 0
	s_add_u32 s58, s28, 0x100
	v_mov_b32_e32 v2, 0
	s_addc_u32 s59, s29, 0
	s_mov_b32 s68, -2
	v_mov_b64_e32 v[2:3], 0
	v_mov_b64_e32 v[4:5], 0
	v_mov_b64_e32 v[6:7], 0
	v_mov_b64_e32 v[8:9], 0
	v_mov_b64_e32 v[10:11], 0
	v_mov_b64_e32 v[12:13], 0
	v_mov_b64_e32 v[14:15], 0
	v_mov_b64_e32 v[16:17], 0
	v_mov_b64_e32 v[18:19], 0
	v_mov_b64_e32 v[20:21], 0
	v_mov_b64_e32 v[22:23], 0
	v_mov_b64_e32 v[24:25], 0
	v_mov_b64_e32 v[26:27], 0
	v_mov_b64_e32 v[28:29], 0
	v_mov_b64_e32 v[30:31], 0
	v_mov_b64_e32 v[32:33], 0
	v_mov_b64_e32 v[34:35], 0
	v_mov_b64_e32 v[36:37], 0
	v_mov_b64_e32 v[38:39], 0
	v_mov_b64_e32 v[40:41], 0
	v_mov_b64_e32 v[42:43], 0
	v_mov_b64_e32 v[44:45], 0
	v_mov_b64_e32 v[46:47], 0
	v_mov_b64_e32 v[48:49], 0
	v_mov_b64_e32 v[50:51], 0
	v_mov_b64_e32 v[52:53], 0
	v_mov_b64_e32 v[54:55], 0
	v_mov_b64_e32 v[56:57], 0
	v_mov_b64_e32 v[58:59], 0
	v_mov_b64_e32 v[60:61], 0
	v_mov_b64_e32 v[62:63], 0
	v_mov_b64_e32 v[64:65], 0
	v_mov_b64_e32 v[66:67], 0
	v_mov_b64_e32 v[68:69], 0
	v_mov_b64_e32 v[70:71], 0
	v_mov_b64_e32 v[72:73], 0
	v_mov_b64_e32 v[74:75], 0
	v_mov_b64_e32 v[76:77], 0
	v_mov_b64_e32 v[78:79], 0
	v_mov_b64_e32 v[80:81], 0
	v_mov_b64_e32 v[82:83], 0
	v_mov_b64_e32 v[84:85], 0
	v_mov_b64_e32 v[86:87], 0
	v_mov_b64_e32 v[88:89], 0
	v_mov_b64_e32 v[90:91], 0
	v_mov_b64_e32 v[92:93], 0
	v_mov_b64_e32 v[94:95], 0
	v_mov_b64_e32 v[96:97], 0
	v_mov_b64_e32 v[98:99], 0
	v_mov_b64_e32 v[100:101], 0
	v_mov_b64_e32 v[102:103], 0
	v_mov_b64_e32 v[104:105], 0
	v_mov_b64_e32 v[106:107], 0
	v_mov_b64_e32 v[108:109], 0
	v_mov_b64_e32 v[110:111], 0
	v_mov_b64_e32 v[112:113], 0
	v_mov_b64_e32 v[114:115], 0
	v_mov_b64_e32 v[116:117], 0
	v_mov_b64_e32 v[118:119], 0
	v_mov_b64_e32 v[120:121], 0
	v_mov_b64_e32 v[122:123], 0
	v_mov_b64_e32 v[124:125], 0
	v_mov_b64_e32 v[126:127], 0
	v_mov_b64_e32 v[128:129], 0

.LBB11_2769:
	s_add_u32 s18, s4, s45
	s_addc_u32 s19, s5, 0
	s_and_b64 s[0:1], s[16:17], exec
	s_cselect_b32 s8, s19, s23
	s_cselect_b32 s9, s18, s22
	s_add_u32 s20, s38, s44
	s_addc_u32 s21, s39, 0
	s_and_b64 s[0:1], s[16:17], exec
	s_cselect_b32 s47, s21, s25
	s_cselect_b32 s56, s20, s24
	s_add_u32 s57, s24, 0x100
	v_mov_b32_e32 v2, 0
	s_addc_u32 s58, s25, 0
	s_mov_b32 s59, -2
	s_waitcnt lgkmcnt(0)
	v_mov_b64_e32 v[2:3], 0
	v_mov_b64_e32 v[4:5], 0
	v_mov_b64_e32 v[6:7], 0
	v_mov_b64_e32 v[8:9], 0
	v_mov_b64_e32 v[10:11], 0
	v_mov_b64_e32 v[12:13], 0
	v_mov_b64_e32 v[14:15], 0
	v_mov_b64_e32 v[16:17], 0
	v_mov_b64_e32 v[18:19], 0
	v_mov_b64_e32 v[20:21], 0
	v_mov_b64_e32 v[22:23], 0
	v_mov_b64_e32 v[24:25], 0
	v_mov_b64_e32 v[26:27], 0
	v_mov_b64_e32 v[28:29], 0
	v_mov_b64_e32 v[30:31], 0
	v_mov_b64_e32 v[32:33], 0
	v_mov_b64_e32 v[34:35], 0
	v_mov_b64_e32 v[36:37], 0
	v_mov_b64_e32 v[38:39], 0
	v_mov_b64_e32 v[40:41], 0
	v_mov_b64_e32 v[42:43], 0
	v_mov_b64_e32 v[44:45], 0
	v_mov_b64_e32 v[46:47], 0
	v_mov_b64_e32 v[48:49], 0
	v_mov_b64_e32 v[50:51], 0
	v_mov_b64_e32 v[52:53], 0
	v_mov_b64_e32 v[54:55], 0
	v_mov_b64_e32 v[56:57], 0
	v_mov_b64_e32 v[58:59], 0
	v_mov_b64_e32 v[60:61], 0
	v_mov_b64_e32 v[62:63], 0
	v_mov_b64_e32 v[64:65], 0
	v_mov_b64_e32 v[66:67], 0
	v_mov_b64_e32 v[68:69], 0
	v_mov_b64_e32 v[70:71], 0
	v_mov_b64_e32 v[72:73], 0
	v_mov_b64_e32 v[74:75], 0
	v_mov_b64_e32 v[76:77], 0
	v_mov_b64_e32 v[78:79], 0
	v_mov_b64_e32 v[80:81], 0
	v_mov_b64_e32 v[82:83], 0
	v_mov_b64_e32 v[84:85], 0
	v_mov_b64_e32 v[86:87], 0
	v_mov_b64_e32 v[88:89], 0
	v_mov_b64_e32 v[90:91], 0
	v_mov_b64_e32 v[92:93], 0
	v_mov_b64_e32 v[94:95], 0
	v_mov_b64_e32 v[96:97], 0
	v_mov_b64_e32 v[98:99], 0
	v_mov_b64_e32 v[100:101], 0
	v_mov_b64_e32 v[102:103], 0
	v_mov_b64_e32 v[104:105], 0
	v_mov_b64_e32 v[106:107], 0
	v_mov_b64_e32 v[108:109], 0
	v_mov_b64_e32 v[110:111], 0
	v_mov_b64_e32 v[112:113], 0
	v_mov_b64_e32 v[114:115], 0
	v_mov_b64_e32 v[116:117], 0
	v_mov_b64_e32 v[118:119], 0
	v_mov_b64_e32 v[120:121], 0
	v_mov_b64_e32 v[122:123], 0
	v_mov_b64_e32 v[124:125], 0
	v_mov_b64_e32 v[126:127], 0
	v_mov_b64_e32 v[128:129], 0
